# v20 + final norm phase: each row loaded one iteration ahead into spare registers (counted waits)
# speedup vs baseline: 1.0070x; 1.0070x over previous
; #define PARAMS const __attribute__((address_space(4))) Params&
; #define BIDX bid_opaque()
; #define GDIM gdim_opaque()
; DI void final_phase(PARAMS P, int wave, int lane) {
;     const int gw = BIDX * 8 + wave, NGW = GDIM * 8;
;     const float* X = (const float*)(P.ws + WS_X);
;     f32x4 gv[4];
; #pragma unroll
;     for (int j = 0; j < 4; ++j) gv[j] = ((const f32x4*)P.in[28])[lane + 64 * j];
;     for (int row = gw; row < MTOT; row += NGW) {
;         int g = 0, lr = row; if (row >= G0ROWS) { g = 1 + (row - G0ROWS) / GROWS; lr = (row - G0ROWS) % GROWS; }
;         float* dst;
;         if (g != 0 || lr < 8192) dst = P.out + O_YP + ((size_t)(4 * g + (lr >> 11)) * 2048 + (lr & 2047)) * D;
;         else if (lr < 8704) dst = P.out + O_YS + (size_t)(lr - 8192) * D;
;         else continue;
;         const f32x4* xr = (const f32x4*)(X + (size_t)row * D);
;         f32x4 v[4]; float ss = 0.f;
; #pragma unroll
;         for (int j = 0; j < 4; ++j) v[j] = xr[lane + 64 * j];
;         if (row >= MMAIN) { const float* part = (const float*)(P.ws + WS_PART);
; #pragma unroll 1
;             for (int kh = 0; kh < NKSL; ++kh) { const f32x4* pr = (const f32x4*)(part + ((size_t)kh * (MTOT - MMAIN) + (row - MMAIN)) * 1024);
; #pragma unroll
;                 for (int j = 0; j < 4; ++j) v[j] += pr[lane + 64 * j]; } }
; #pragma unroll
;         for (int j = 0; j < 4; ++j) ss += (v[j][0] * v[j][0] + v[j][1] * v[j][1]) + (v[j][2] * v[j][2] + v[j][3] * v[j][3]);
;         const float rs = rsqrtf(wave_sum(ss) * (1.f / D) + EPS);
; #pragma unroll
;         for (int j = 0; j < 4; ++j) ((f32x4*)dst)[lane + 64 * j] = v[j] * rs * gv[j];
;     }
.LBB0_924:
	s_and_b64 vcc, exec, s[68:69]
	s_cbranch_vccz .LBB0_940
	s_waitcnt vmcnt(0)
	v_mov_b32_e32 v0, v228
	v_mov_b32_e32 v1, v228
	s_nop 0
	v_readfirstlane_b32 s0, v1
	s_ashr_i32 s1, s0, 6
	s_mov_b32 s0, s82
	s_lshl_b32 s2, s0, 3
	s_add_i32 s8, s2, s1
	s_mov_b32 s0, s92
	s_cmp_gt_i32 s8, 0x82ff
	s_cbranch_scc1 .LBB0_939
	s_load_dwordx4 s[4:7], s[18:19], 0xe0
	s_load_dwordx2 s[10:11], s[18:19], 0xf0
	s_waitcnt vmcnt(0)
	v_and_b32_e32 v16, 63, v0
	v_lshlrev_b32_e32 v32, 4, v16
	s_lshl_b32 s0, s0, 3
	s_waitcnt lgkmcnt(0)
	global_load_dwordx4 v[0:3], v32, s[4:5]
	global_load_dwordx4 v[4:7], v32, s[4:5] offset:1024
	global_load_dwordx4 v[8:11], v32, s[4:5] offset:2048
	global_load_dwordx4 v[12:15], v32, s[4:5] offset:3072
	s_add_u32 s1, s6, 0x8000000
	v_lshl_add_u64 v[34:35], s[10:11], 0, v[32:33]
	s_mov_b64 s[4:5], 0x1c67a000
	s_addc_u32 s2, s7, 0
	v_lshl_add_u64 v[36:37], v[34:35], 0, s[4:5]
	v_lshlrev_b32_e32 v32, 4, v16
	s_mov_b32 s10, s8
	s_ashr_i32 s11, s10, 31
	s_lshl_b64 s[10:11], s[10:11], 12
	v_lshl_add_u64 v[128:129], v[34:35], 0, s[10:11]
	global_load_dwordx4 v[112:115], v[128:129], off
	global_load_dwordx4 v[116:119], v[128:129], off offset:1024
	global_load_dwordx4 v[120:123], v[128:129], off offset:2048
	global_load_dwordx4 v[124:127], v[128:129], off offset:3072
	s_waitcnt vmcnt(0)
	s_branch .LBB0_929
.LBB0_927:
	v_pk_mul_f32 v[42:43], v[30:31], v[30:31]
	v_pk_mul_f32 v[44:45], v[28:29], v[28:29]
	v_pk_mul_f32 v[38:39], v[26:27], v[26:27]
	v_pk_mul_f32 v[40:41], v[24:25], v[24:25]
	v_pk_mov_b32 v[46:47], v[44:45], v[42:43] op_sel:[1,0]
	v_mov_b32_e32 v45, v43
	v_pk_add_f32 v[42:43], v[46:47], v[44:45]
	v_pk_mov_b32 v[44:45], v[40:41], v[38:39] op_sel:[1,0]
	v_mov_b32_e32 v41, v39
	v_pk_add_f32 v[38:39], v[44:45], v[40:41]
	v_pk_add_f32 v[42:43], v[42:43], v[42:43] op_sel_hi:[0,1]
	v_pk_add_f32 v[38:39], v[38:39], v[38:39] op_sel_hi:[0,1]
	v_mul_f32_e32 v38, v20, v20
	v_pk_fma_f32 v[40:41], v[20:21], v[20:21], v[38:39] op_sel_hi:[1,1,0]
	v_mul_f32_e32 v38, v22, v22
	v_pk_fma_f32 v[44:45], v[22:23], v[22:23], v[38:39] op_sel_hi:[1,1,0]
	v_mul_f32_e32 v40, v16, v16
	v_mul_f32_e32 v44, v17, v17
	v_mul_f32_e32 v42, v18, v18
	v_mul_f32_e32 v38, v19, v19
	v_pk_add_f32 v[40:41], v[40:41], v[44:45]
	v_pk_add_f32 v[38:39], v[42:43], v[38:39]
	s_nop 0
	v_pk_add_f32 v[38:39], v[40:41], v[38:39]
	s_nop 0
	v_add_f32_e32 v38, v38, v39
	s_nop 1
	v_add_f32_dpp v38, v38, v38 quad_perm:[1,0,3,2] row_mask:0xf bank_mask:0xf bound_ctrl:1
	s_nop 1
	v_add_f32_dpp v38, v38, v38 quad_perm:[2,3,0,1] row_mask:0xf bank_mask:0xf bound_ctrl:1
	s_nop 1
	v_add_f32_dpp v38, v38, v38 row_half_mirror row_mask:0xf bank_mask:0xf bound_ctrl:1
	s_nop 1
	v_add_f32_dpp v38, v38, v38 row_mirror row_mask:0xf bank_mask:0xf bound_ctrl:1
	s_nop 0
	v_readlane_b32 s3, v38, 16
	v_readlane_b32 s9, v38, 48
	v_readlane_b32 s10, v38, 0
	v_readlane_b32 s11, v38, 32
	v_mov_b32_e32 v38, s3
	v_mov_b32_e32 v39, s9
	v_pk_add_f32 v[38:39], s[10:11], v[38:39]
	s_nop 0
	v_add_f32_e32 v38, v38, v39
	v_fmamk_f32 v38, v38, 0x3a800000, v229
	v_mul_f32_e32 v39, 0x4b800000, v38
	v_cmp_gt_f32_e32 vcc, s81, v38
	s_nop 1
	v_cndmask_b32_e32 v38, v38, v39, vcc
	v_rsq_f32_e32 v38, v38
	s_nop 0
	v_mul_f32_e32 v39, 0x45800000, v38
	v_cndmask_b32_e32 v38, v38, v39, vcc
	v_pk_mul_f32 v[28:29], v[28:29], v[38:39] op_sel_hi:[1,0]
	v_pk_mul_f32 v[30:31], v[30:31], v[38:39] op_sel_hi:[1,0]
	v_pk_mul_f32 v[24:25], v[24:25], v[38:39] op_sel_hi:[1,0]
	v_pk_mul_f32 v[26:27], v[26:27], v[38:39] op_sel_hi:[1,0]
	v_pk_mul_f32 v[20:21], v[20:21], v[38:39] op_sel_hi:[1,0]
	v_pk_mul_f32 v[22:23], v[22:23], v[38:39] op_sel_hi:[1,0]
	v_pk_mul_f32 v[16:17], v[16:17], v[38:39] op_sel_hi:[1,0]
	v_pk_mul_f32 v[18:19], v[18:19], v[38:39] op_sel_hi:[1,0]
	v_pk_mul_f32 v[30:31], v[2:3], v[30:31]
	v_pk_mul_f32 v[28:29], v[0:1], v[28:29]
	v_pk_mul_f32 v[26:27], v[6:7], v[26:27]
	v_pk_mul_f32 v[24:25], v[4:5], v[24:25]
	v_pk_mul_f32 v[22:23], v[10:11], v[22:23]
	v_pk_mul_f32 v[20:21], v[8:9], v[20:21]
	v_pk_mul_f32 v[18:19], v[14:15], v[18:19]
	v_pk_mul_f32 v[16:17], v[12:13], v[16:17]
	global_store_dwordx4 v32, v[28:31], s[4:5]
	global_store_dwordx4 v32, v[24:27], s[4:5] offset:1024
	global_store_dwordx4 v32, v[20:23], s[4:5] offset:2048
	global_store_dwordx4 v32, v[16:19], s[4:5] offset:3072

; DI void final_phase(PARAMS P, int wave, int lane) {
;     ...
;     for (int row = gw; row < MTOT; row += NGW) {
;         int g = 0, lr = row; if (row >= G0ROWS) { g = 1 + (row - G0ROWS) / GROWS; lr = (row - G0ROWS) % GROWS; }
;         float* dst;
;         if (g != 0 || lr < 8192) dst = P.out + O_YP + ((size_t)(4 * g + (lr >> 11)) * 2048 + (lr & 2047)) * D;
;         else if (lr < 8704) dst = P.out + O_YS + (size_t)(lr - 8192) * D;
;         else continue;
;         const f32x4* xr = (const f32x4*)(X + (size_t)row * D);
;         f32x4 v[4]; float ss = 0.f;
; #pragma unroll
;         for (int j = 0; j < 4; ++j) v[j] = xr[lane + 64 * j];
.LBB0_929:
	s_waitcnt vmcnt(4)
	v_mov_b64_e32 v[28:29], v[112:113]
	v_mov_b64_e32 v[30:31], v[114:115]
	v_mov_b64_e32 v[24:25], v[116:117]
	v_mov_b64_e32 v[26:27], v[118:119]
	v_mov_b64_e32 v[20:21], v[120:121]
	v_mov_b64_e32 v[22:23], v[122:123]
	v_mov_b64_e32 v[16:17], v[124:125]
	v_mov_b64_e32 v[18:19], v[126:127]
	s_add_i32 s10, s8, s0
	s_cmp_gt_i32 s10, 0x82ff
	s_cbranch_scc1 .Lfin_nopf
	s_ashr_i32 s11, s10, 31
	s_lshl_b64 s[10:11], s[10:11], 12
	v_lshl_add_u64 v[128:129], v[34:35], 0, s[10:11]
	global_load_dwordx4 v[112:115], v[128:129], off
	global_load_dwordx4 v[116:119], v[128:129], off offset:1024
	global_load_dwordx4 v[120:123], v[128:129], off offset:2048
	global_load_dwordx4 v[124:127], v[128:129], off offset:3072

; DI void final_phase(PARAMS P, int wave, int lane) {
;     ...
;         const f32x4* xr = (const f32x4*)(X + (size_t)row * D);
;         f32x4 v[4]; float ss = 0.f;
; #pragma unroll
;         for (int j = 0; j < 4; ++j) v[j] = xr[lane + 64 * j];
;         if (row >= MMAIN) { const float* part = (const float*)(P.ws + WS_PART);
.LBB0_936:
	s_cmp_lt_i32 s8, 0x8000
	s_cbranch_scc1 .LBB0_927
	s_movk_i32 s3, 0x8000

; DI void final_phase(PARAMS P, int wave, int lane) {
;     ...
;     for (int row = gw; row < MTOT; row += NGW) {
;         int g = 0, lr = row; if (row >= G0ROWS) { g = 1 + (row - G0ROWS) / GROWS; lr = (row - G0ROWS) % GROWS; }
;         float* dst;
;         if (g != 0 || lr < 8192) dst = P.out + O_YP + ((size_t)(4 * g + (lr >> 11)) * 2048 + (lr & 2047)) * D;
;         else if (lr < 8704) dst = P.out + O_YS + (size_t)(lr - 8192) * D;
;         else continue;
.Lfin_skip:
	s_waitcnt vmcnt(0)
	s_branch .LBB0_928
